# c_phase QK/PV LDS reads batched; GU epilogue row sum-of-squares prefetched via LDS-DMA into extra static LDS
# speedup vs baseline: 1.0207x; 1.0057x over previous
; #define LAS __attribute__((address_space(3)))
; __device__ __forceinline__ void qk_tile(f32x16& p0, f32x16& p1, const ldsp Kt, const bf16x8 (&qr)[4], const f32x16& cin, int r32, int hi) {
;     const ldsp kb = Kt + hi * 1024; const int ks = (r32 ^ (2 * hi)) << 4;
; #pragma unroll
;     for (int d0 = 0; d0 < 4; ++d0) {
;         const ldsp kp = kb + d0 * 2048 + (ks ^ (64 * d0));
;         const bf16x8 b0 = *(const LAS bf16x8*)(kp), b1 = *(const LAS bf16x8*)(kp + 512);
;         if (d0 == 0) { p0 = __builtin_amdgcn_mfma_f32_32x32x16_bf16(b0, qr[0], cin, 0, 0, 0); p1 = __builtin_amdgcn_mfma_f32_32x32x16_bf16(b1, qr[0], cin, 0, 0, 0); }
;         else { p0 = __builtin_amdgcn_mfma_f32_32x32x16_bf16(b0, qr[d0], p0, 0, 0, 0); p1 = __builtin_amdgcn_mfma_f32_32x32x16_bf16(b1, qr[d0], p1, 0, 0, 0); }
;     }
;     asm volatile("s_nop 15\n\ts_nop 7" : "+v"(p0), "+v"(p1));
; }
.LBB0_1038:
	s_and_b32 s79, s77, 0x8000
	s_cmp_gt_i32 s73, s75
	s_cselect_b64 s[8:9], -1, 0
	s_add_i32 s10, s73, 63
	s_cmp_lt_i32 s10, s76
	s_cselect_b64 s[10:11], -1, 0
	s_or_b64 s[8:9], s[8:9], s[10:11]
	s_and_b64 vcc, exec, s[8:9]
	s_cbranch_vccnz .LBB0_1062
	s_add_i32 s33, s94, s79
	v_add_u32_e32 v96, s33, v187
	v_add_u32_e32 v97, v96, v208
	v_xor_b32_e32 v98, 64, v208
	v_xor_b32_e32 v99, 0x80, v208
	v_xor_b32_e32 v100, 0xc0, v208
	v_add_u32_e32 v98, v96, v98
	v_add_u32_e32 v99, v96, v99
	v_add_u32_e32 v100, v96, v100
	ds_read_b128 v[64:67], v97
	ds_read_b128 v[68:71], v97 offset:512
	ds_read_b128 v[72:75], v98 offset:2048
	ds_read_b128 v[76:79], v98 offset:2560
	ds_read_b128 v[80:83], v99 offset:4096
	ds_read_b128 v[84:87], v99 offset:4608
	ds_read_b128 v[88:91], v100 offset:6144
	ds_read_b128 v[92:95], v100 offset:6656
	v_add_u32_e32 v176, 0x80, v213
	v_cmp_lt_i32_e32 vcc, 0, v213
	s_cmp_lg_u64 vcc, 0
	v_cmp_gt_i32_e32 vcc, 63, v176
	s_cselect_b64 s[10:11], -1, 0
	s_cmp_eq_u64 vcc, 0
	s_cselect_b64 s[8:9], -1, 0
	s_cmp_lg_u64 vcc, 0
	s_cselect_b64 s[12:13], -1, 0
	s_and_b64 s[12:13], s[10:11], s[12:13]
	s_andn2_b64 vcc, exec, s[12:13]
	s_waitcnt lgkmcnt(7)
	v_mfma_f32_32x32x16_bf16 v[112:127], v[64:67], v[160:163], v[48:63]
	s_waitcnt lgkmcnt(6)
	v_mfma_f32_32x32x16_bf16 v[96:111], v[68:71], v[160:163], v[48:63]
	s_waitcnt lgkmcnt(5)
	v_mfma_f32_32x32x16_bf16 v[112:127], v[72:75], v[164:167], v[112:127]
	s_waitcnt lgkmcnt(4)
	v_mfma_f32_32x32x16_bf16 v[96:111], v[76:79], v[164:167], v[96:111]
	s_waitcnt lgkmcnt(3)
	v_mfma_f32_32x32x16_bf16 v[112:127], v[80:83], v[168:171], v[112:127]
	s_waitcnt lgkmcnt(2)
	v_mfma_f32_32x32x16_bf16 v[96:111], v[84:87], v[168:171], v[96:111]
	s_waitcnt lgkmcnt(1)
	v_mfma_f32_32x32x16_bf16 v[112:127], v[88:91], v[172:175], v[112:127]
	s_waitcnt lgkmcnt(0)
	v_mfma_f32_32x32x16_bf16 v[96:111], v[92:95], v[172:175], v[96:111]
	s_nop 15
	s_nop 7
	s_cbranch_vccz .LBB0_1046
	s_and_b64 vcc, exec, s[8:9]
	s_cbranch_vccz .LBB0_1073
	s_nop 6
	v_mov_b64_e32 v[64:65], v[112:113]
	s_nop 0
	v_mov_b64_e32 v[80:81], v[96:97]
	s_mov_b64 s[8:9], 0
	s_and_b64 vcc, exec, s[10:11]
	s_mov_b64 s[96:97], 0
	v_mov_b64_e32 v[66:67], v[114:115]
	v_mov_b64_e32 v[68:69], v[116:117]
	v_mov_b64_e32 v[70:71], v[118:119]
	v_mov_b64_e32 v[72:73], v[120:121]
	v_mov_b64_e32 v[74:75], v[122:123]
	v_mov_b64_e32 v[76:77], v[124:125]
	v_mov_b64_e32 v[78:79], v[126:127]
	v_mov_b64_e32 v[82:83], v[98:99]
	v_mov_b64_e32 v[84:85], v[100:101]
	v_mov_b64_e32 v[86:87], v[102:103]
	v_mov_b64_e32 v[88:89], v[104:105]
	v_mov_b64_e32 v[90:91], v[106:107]
	v_mov_b64_e32 v[92:93], v[108:109]
	v_mov_b64_e32 v[94:95], v[110:111]
	s_cbranch_vccz .LBB0_1043
	v_add_u32_e32 v214, v253, v213
	v_cmp_gt_i32_e32 vcc, 1, v214
	v_mov_b32_e32 v95, v111
	s_nop 0
	v_cndmask_b32_e32 v64, v216, v112, vcc
	v_cmp_gt_i32_e32 vcc, 33, v214
	s_nop 1
	v_cndmask_b32_e32 v80, v216, v96, vcc
	v_cmp_gt_i32_e32 vcc, 2, v214
	s_nop 1
	v_cndmask_b32_e32 v65, v216, v113, vcc
	v_cmp_gt_i32_e32 vcc, 34, v214
	s_nop 1
	v_cndmask_b32_e32 v81, v216, v97, vcc
	v_cmp_gt_i32_e32 vcc, 3, v214
	s_nop 1
	v_cndmask_b32_e32 v66, v216, v114, vcc
	v_cmp_gt_i32_e32 vcc, 35, v214
	s_nop 1
	v_cndmask_b32_e32 v82, v216, v98, vcc
	v_cmp_gt_i32_e32 vcc, 4, v214
	s_nop 1
	v_cndmask_b32_e32 v67, v216, v115, vcc
	v_cmp_gt_i32_e32 vcc, 36, v214
	s_nop 1
	v_cndmask_b32_e32 v83, v216, v99, vcc
	v_cmp_gt_i32_e32 vcc, 9, v214
	s_nop 1
	v_cndmask_b32_e32 v68, v216, v116, vcc
	v_cmp_gt_i32_e32 vcc, 41, v214
	s_nop 1
	v_cndmask_b32_e32 v84, v216, v100, vcc
	v_cmp_gt_i32_e32 vcc, 10, v214
	s_nop 1
	v_cndmask_b32_e32 v69, v216, v117, vcc
	v_cmp_gt_i32_e32 vcc, 42, v214
	s_nop 1
	v_cndmask_b32_e32 v85, v216, v101, vcc
	v_cmp_gt_i32_e32 vcc, 11, v214
	s_nop 1
	v_cndmask_b32_e32 v70, v216, v118, vcc
	v_cmp_gt_i32_e32 vcc, 43, v214
	s_nop 1
	v_cndmask_b32_e32 v86, v216, v102, vcc
	v_cmp_gt_i32_e32 vcc, 12, v214
	s_nop 1
	v_cndmask_b32_e32 v71, v216, v119, vcc
	v_cmp_gt_i32_e32 vcc, 44, v214
	s_nop 1
	v_cndmask_b32_e32 v87, v216, v103, vcc
	v_cmp_gt_i32_e32 vcc, 17, v214
	s_nop 1
	v_cndmask_b32_e32 v72, v216, v120, vcc
	v_cmp_gt_i32_e32 vcc, 49, v214
	s_nop 1
	v_cndmask_b32_e32 v88, v216, v104, vcc
	v_cmp_gt_i32_e32 vcc, 18, v214
	s_nop 1
	v_cndmask_b32_e32 v73, v216, v121, vcc
	v_cmp_gt_i32_e32 vcc, 50, v214
	s_nop 1
	v_cndmask_b32_e32 v89, v216, v105, vcc
	v_cmp_gt_i32_e32 vcc, 19, v214
	s_nop 1
	v_cndmask_b32_e32 v74, v216, v122, vcc
	v_cmp_gt_i32_e32 vcc, 51, v214
	s_nop 1
	v_cndmask_b32_e32 v90, v216, v106, vcc
	v_cmp_gt_i32_e32 vcc, 20, v214
	s_nop 1
	v_cndmask_b32_e32 v75, v216, v123, vcc
	v_cmp_gt_i32_e32 vcc, 52, v214
	s_nop 1
	v_cndmask_b32_e32 v91, v216, v107, vcc
	v_cmp_gt_i32_e32 vcc, 25, v214
	s_nop 1
	v_cndmask_b32_e32 v76, v216, v124, vcc
	v_cmp_gt_i32_e32 vcc, 57, v214
	s_nop 1
	v_cndmask_b32_e32 v92, v216, v108, vcc
	v_cmp_gt_i32_e32 vcc, 26, v214
	s_nop 1
	v_cndmask_b32_e32 v77, v216, v125, vcc
	v_cmp_gt_i32_e32 vcc, 58, v214
	s_nop 1
	v_cndmask_b32_e32 v93, v216, v109, vcc
	v_cmp_gt_i32_e32 vcc, 27, v214
	s_nop 1
	v_cndmask_b32_e32 v78, v216, v126, vcc
	v_cmp_gt_i32_e32 vcc, 59, v214
	s_nop 1
	v_cndmask_b32_e32 v94, v216, v110, vcc
	v_cmp_gt_i32_e32 vcc, 28, v214
	s_nop 1
	v_cndmask_b32_e32 v79, v216, v127, vcc
	v_cmp_lt_i32_e32 vcc, 59, v214
	s_and_b64 s[96:97], vcc, exec

; #define LAS __attribute__((address_space(3)))
; __device__ __forceinline__ unsigned pk2(float lo, float hi) { f32x2_t v = {lo, hi}; bf16x2_t b = __builtin_convertvector(v, bf16x2_t); return __builtin_bit_cast(unsigned, b); }
; __device__ __forceinline__ float fexp2(float x) { return __builtin_amdgcn_exp2f(x); }
; __device__ __forceinline__ void sm_update(f32x16& p0, f32x16& p1, float& mref, f32x16& negm, float& l, f32x16 (&o)[2], bool first, LAS float* wsf, int r32, int hi) {
;     ...
;     float s = 0.f;
; #pragma unroll
;     for (int r = 0; r < 16; ++r) { p0[r] = fexp2(p0[r]); p1[r] = fexp2(p1[r]); s += p0[r] + p1[r]; }
;     l += s;
; }
; __device__ __forceinline__ s16x4 vtr(const ldsp p) { typedef short v4i16_t __attribute__((ext_vector_type(4))); return __builtin_bit_cast(s16x4, __builtin_amdgcn_ds_read_tr16_b64_v4i16((LAS v4i16_t*)p)); }
; __device__ __forceinline__ void pv_tile(f32x16 (&o)[2], const ldsp Vt, const f32x16& p0, const f32x16& p1, int lane, int hi) {
;     u32x4 pw[4];
;     pw[0] = (u32x4){pk2(p0[0], p0[1]), pk2(p0[2], p0[3]), pk2(p0[4], p0[5]), pk2(p0[6], p0[7])};
;     pw[1] = (u32x4){pk2(p0[8], p0[9]), pk2(p0[10], p0[11]), pk2(p0[12], p0[13]), pk2(p0[14], p0[15])};
;     pw[2] = (u32x4){pk2(p1[0], p1[1]), pk2(p1[2], p1[3]), pk2(p1[4], p1[5]), pk2(p1[6], p1[7])};
;     pw[3] = (u32x4){pk2(p1[8], p1[9]), pk2(p1[10], p1[11]), pk2(p1[12], p1[13]), pk2(p1[14], p1[15])};
;     const ldsp vp = Vt + ((lane >> 4) & 1) * 32 + (lane & 3) * 8 + (4 * hi + ((lane & 15) >> 2)) * 64;
; #pragma unroll
;     for (int d0 = 0; d0 < 2; ++d0)
; #pragma unroll
;         for (int ks = 0; ks < 4; ++ks) {
;             const s16x4 lo = vtr(vp + d0 * 4096 + ks * 1024), hh = vtr(vp + d0 * 4096 + ks * 1024 + 512);
;             const bf16x8 vf = (bf16x8){lo[0], lo[1], lo[2], lo[3], hh[0], hh[1], hh[2], hh[3]};
;             o[d0] = __builtin_amdgcn_mfma_f32_32x32x16_bf16(__builtin_bit_cast(bf16x8, pw[ks]), vf, o[d0], 0, 0, 0);
;         }
.LBB0_1061:
	v_add3_u32 v107, s33, v247, v248
	v_add3_u32 v107, v107, v249, v250
	ds_read_b64_tr_b16 v[108:109], v107 offset:8192
	ds_read_b64_tr_b16 v[110:111], v107 offset:8704
	ds_read_b64_tr_b16 v[112:113], v107 offset:9216
	ds_read_b64_tr_b16 v[114:115], v107 offset:9728
	ds_read_b64_tr_b16 v[116:117], v107 offset:10240
	ds_read_b64_tr_b16 v[118:119], v107 offset:10752
	ds_read_b64_tr_b16 v[120:121], v107 offset:11264
	ds_read_b64_tr_b16 v[122:123], v107 offset:11776
	ds_read_b64_tr_b16 v[124:125], v107 offset:12288
	ds_read_b64_tr_b16 v[126:127], v107 offset:12800
	v_exp_f32_e32 v104, v64
	v_exp_f32_e32 v105, v80
	v_exp_f32_e32 v176, v65
	v_exp_f32_e32 v96, v81
	v_exp_f32_e32 v106, v82
	v_add_f32_e32 v97, v105, v104
	v_exp_f32_e32 v80, v83
	v_pk_add_f32 v[64:65], v[96:97], v[176:177]
	v_exp_f32_e32 v97, v66
	v_pk_add_f32 v[64:65], v[64:65], v[64:65] op_sel_hi:[0,1]
	v_exp_f32_e32 v64, v67
	v_exp_f32_e32 v82, v85
	v_add_f32_e32 v81, v106, v97
	v_exp_f32_e32 v98, v87
	v_pk_add_f32 v[66:67], v[80:81], v[64:65]
	v_exp_f32_e32 v65, v68
	v_pk_add_f32 v[66:67], v[66:67], v[66:67] op_sel_hi:[0,1]
	v_exp_f32_e32 v81, v84
	v_exp_f32_e32 v66, v69
	v_exp_f32_e32 v72, v72
	v_exp_f32_e32 v100, v89
	v_add_f32_e32 v83, v81, v65
	v_pk_add_f32 v[68:69], v[82:83], v[66:67]
	v_exp_f32_e32 v67, v70
	v_pk_add_f32 v[84:85], v[68:69], v[68:69] op_sel_hi:[0,1]
	v_exp_f32_e32 v83, v86
	v_exp_f32_e32 v84, v71
	v_exp_f32_e32 v102, v91
	v_cvt_pk_bf16_f32 v70, v65, v66
	v_add_f32_e32 v99, v83, v67
	v_pk_add_f32 v[68:69], v[98:99], v[84:85]
	v_exp_f32_e32 v85, v88
	v_pk_add_f32 v[86:87], v[68:69], v[68:69] op_sel_hi:[0,1]
	v_exp_f32_e32 v86, v73
	v_exp_f32_e32 v73, v74
	v_add_f32_e32 v101, v85, v72
	v_exp_f32_e32 v99, v92
	v_pk_add_f32 v[68:69], v[100:101], v[86:87]
	v_exp_f32_e32 v87, v90
	v_pk_add_f32 v[88:89], v[68:69], v[68:69] op_sel_hi:[0,1]
	v_exp_f32_e32 v88, v75
	v_exp_f32_e32 v90, v93
	v_add_f32_e32 v103, v87, v73
	v_exp_f32_e32 v92, v95
	v_pk_add_f32 v[68:69], v[102:103], v[88:89]
	v_exp_f32_e32 v89, v76
	v_pk_add_f32 v[74:75], v[68:69], v[68:69] op_sel_hi:[0,1]
	v_exp_f32_e32 v74, v77
	v_cvt_pk_bf16_f32 v71, v67, v84
	v_add_f32_e32 v91, v99, v89
	v_cvt_pk_bf16_f32 v72, v72, v86
	v_pk_add_f32 v[68:69], v[90:91], v[74:75]
	v_exp_f32_e32 v75, v78
	v_pk_add_f32 v[76:77], v[68:69], v[68:69] op_sel_hi:[0,1]
	v_exp_f32_e32 v91, v94
	v_exp_f32_e32 v76, v79
	v_cvt_pk_bf16_f32 v78, v81, v82
	v_cvt_pk_bf16_f32 v79, v83, v98
	v_add_f32_e32 v93, v91, v75
	v_pk_add_f32 v[68:69], v[92:93], v[76:77]
	v_cvt_pk_bf16_f32 v77, v106, v80
	v_add_f32_e32 v68, v68, v69
	v_add_f32_e32 v181, v181, v68
	v_cvt_pk_bf16_f32 v68, v104, v176
	v_cvt_pk_bf16_f32 v69, v97, v64
	ds_read_b64_tr_b16 v[80:81], v107 offset:13312
	ds_read_b64_tr_b16 v[82:83], v107 offset:13824
	s_waitcnt lgkmcnt(10)
	v_mfma_f32_32x32x16_bf16 v[32:47], v[68:71], v[108:111], v[32:47]
	v_cvt_pk_bf16_f32 v73, v73, v88
	v_cvt_pk_bf16_f32 v74, v89, v74
	v_cvt_pk_bf16_f32 v75, v75, v76
	ds_read_b64_tr_b16 v[108:109], v107 offset:14336
	ds_read_b64_tr_b16 v[110:111], v107 offset:14848
	v_cvt_pk_bf16_f32 v76, v105, v96
	v_cvt_pk_bf16_f32 v64, v85, v100
	v_cvt_pk_bf16_f32 v65, v87, v102
	s_waitcnt lgkmcnt(10)
	v_mfma_f32_32x32x16_bf16 v[32:47], v[72:75], v[112:115], v[32:47]
	ds_read_b64_tr_b16 v[112:113], v107 offset:15360
	ds_read_b64_tr_b16 v[114:115], v107 offset:15872
	v_cvt_pk_bf16_f32 v66, v99, v90
	v_cvt_pk_bf16_f32 v67, v91, v92
	s_mov_b64 s[88:89], -1
	s_waitcnt lgkmcnt(10)
	v_mfma_f32_32x32x16_bf16 v[32:47], v[76:79], v[116:119], v[32:47]
	s_waitcnt lgkmcnt(8)
	v_mfma_f32_32x32x16_bf16 v[32:47], v[64:67], v[120:123], v[32:47]
	s_waitcnt lgkmcnt(6)
	v_mfma_f32_32x32x16_bf16 v[16:31], v[68:71], v[124:127], v[16:31]
	s_waitcnt lgkmcnt(4)
	v_mfma_f32_32x32x16_bf16 v[16:31], v[72:75], v[80:83], v[16:31]
	s_waitcnt lgkmcnt(2)
	v_mfma_f32_32x32x16_bf16 v[16:31], v[76:79], v[108:111], v[16:31]
	s_waitcnt lgkmcnt(0)
	v_mfma_f32_32x32x16_bf16 v[16:31], v[64:67], v[112:115], v[16:31]

; #define PG8_STAGE(bufoff, gbase, voff) do { _Pragma("unroll") for (int _i = 0; _i < 2; ++_i) \
;         __builtin_amdgcn_global_load_lds((const unsigned*)((const char*)(gbase) + (voff)[_i]), (PG8_LAS unsigned*)(lds + (bufoff) + ldsw + _i * 8192), 16, 0, 0); } while (0)
; #define PG8_WAIT_V(n) asm volatile("s_waitcnt vmcnt(" #n ")" ::: "memory")
; #define PG8_BAR __builtin_amdgcn_s_barrier()
; #define GAS_ __attribute__((address_space(1)))
; template <class Epi, class Sched, bool ALIGN_EPI = false, bool SP2 = false>
; __device__ __forceinline__ void gemm_phase(PG8_LAS unsigned char* lds, const Gemm g, const Sched& S, const Epi& E, int wave0) {
;     ...
;         PG8_STAGE(PG8_SB(0, 0), cB, voffB); PG8_STAGE(PG8_SB(0, 1), cB + hstep, voffB); PG8_STAGE(PG8_SA(0, 0), cA, voffA); PG8_STAGE(PG8_SA(0, 1), cA + hstepA, voffA);
;         if (wr == 1) PG8_BAR;
;         PG8_WAIT_V(2); PG8_BAR;
;         PG8_STAGE(PG8_SB(1, 0), cB + kstep, voffB); PG8_STAGE(PG8_SA(1, 0), cA + kstepA, voffA); PG8_STAGE(PG8_SB(1, 1), cB + hstep + kstep, voffB);
;         PG8_WAIT_V(6); PG8_BAR;
; __device__ __forceinline__ void rows_rstd(float (&rs)[2][4], const float* SS, int row0, int fq) {
;     f32x4 q[2][4];
; #pragma unroll
;     for (int ai = 0; ai < 2; ++ai)
; #pragma unroll
;         for (int m = 0; m < 4; ++m) q[ai][m] = *(const GAS_ f32x4*)(SS + (size_t)(row0 + ai * 128 + m * 16) * 16 + fq * 4);
.LBB0_1226:
	s_add_u32 s12, s6, 0xc800000
	s_addc_u32 s13, s7, 0
	v_bfe_u32 v31, v30, 4, 2
	s_lshl_b32 s8, s8, 5
	v_and_b32_e32 v33, 15, v30
	v_lshlrev_b32_e32 v32, 4, v31
	v_lshlrev_b32_e32 v30, 2, v30
	s_and_b32 s16, s8, 0x60
	s_add_i32 m0, s29, 0x18000
	v_lshl_add_u64 v[22:23], v[22:23], 0, s[70:71]
	v_lshl_or_b32 v217, s9, 6, v33
	v_lshl_or_b32 v33, v33, 6, v32
	s_lshl_b32 s9, s9, 13
	v_and_b32_e32 v30, 32, v30
	s_lshl_b32 s8, s16, 7
	s_waitcnt vmcnt(2)
	s_barrier
	global_load_lds_dwordx4 v[22:23], off
	v_lshl_add_u64 v[20:21], v[20:21], 0, s[70:71]
	s_add_i32 m0, s29, 0x1a000
	s_add_i32 s35, s29, 0x8000
	s_add_i32 s36, s29, 0xa000
	v_bitop3_b32 v218, v33, s8, v30 bitop3:0xde
	global_load_lds_dwordx4 v[20:21], off
	v_lshl_add_u64 v[16:17], v[16:17], 0, s[70:71]
	s_mov_b32 m0, s35
	s_add_u32 s8, s0, 0x40080
	v_bitop3_b32 v34, v33, s9, v30 bitop3:0xde
	global_load_lds_dwordx4 v[16:17], off
	v_lshl_add_u64 v[16:17], v[18:19], 0, s[70:71]
	s_mov_b32 m0, s36
	s_addc_u32 s9, s1, 0
	global_load_lds_dwordx4 v[16:17], off
	s_add_i32 m0, s29, 0x1c000
	v_lshl_add_u64 v[16:17], s[8:9], 0, v[176:177]
	global_load_lds_dwordx4 v[16:17], off
	v_lshl_add_u64 v[16:17], s[8:9], 0, v[182:183]
	s_add_i32 m0, s29, 0x1e000
	v_mov_b32_e32 v33, v177
	global_load_lds_dwordx4 v[16:17], off
	v_lshl_add_u64 v[16:17], s[6:7], 0, v[32:33]
	s_mov_b64 s[6:7], 0x2d000000
	v_lshl_add_u64 v[188:189], v[16:17], 0, s[6:7]
	v_lshlrev_b32_e32 v16, 14, v24
	v_and_b32_e32 v16, 0xffff8000, v16
	v_lshl_add_u32 v16, v25, 11, v16
	v_and_b32_e32 v17, 1, v24
	v_lshl_or_b32 v16, v17, 6, v16
	v_lshl_add_u32 v190, v26, 1, v16
	v_lshlrev_b32_e32 v16, 14, v28
	v_and_b32_e32 v16, 0xffff8000, v16
	s_waitcnt vmcnt(6)
	v_lshl_add_u32 v16, v27, 11, v16
	v_and_b32_e32 v17, 1, v28
	s_cmpk_lt_u32 s2, 0x100
	v_lshl_or_b32 v16, v17, 6, v16
	v_readlane_b32 s6, v254, 51
	s_cselect_b64 s[14:15], -1, 0
	v_lshl_or_b32 v219, v31, 3, s16
	s_waitcnt vmcnt(0)
	v_mov_b32_e32 v191, v177
	v_lshl_add_u32 v192, v29, 1, v16
	v_mov_b32_e32 v193, v177
	s_mov_b32 s37, 0
	v_add_u32_e32 v220, 0, v34
	v_readlane_b32 s2, v254, 50
	s_cmp_eq_u64 s[10:11], 0
	s_cbranch_scc1 .Lgu_ss_skip0
	v_readlane_b32 s98, v219, 0
	s_nop 1
	s_lshr_b32 s98, s98, 5
	s_and_b32 s99, s98, 1
	s_lshl_b32 s99, s99, 7
	s_lshr_b32 s100, s98, 1
	s_lshl_b32 s100, s100, 6
	s_add_i32 s99, s99, s100
	s_lshl_b32 s100, s6, 8
	s_add_i32 s99, s99, s100
	v_and_b32_e32 v16, 15, v217
	v_add_u32_e32 v16, s99, v16
	v_lshlrev_b32_e32 v16, 6, v16
	v_mov_b32_e32 v17, 0
	v_lshl_add_u64 v[16:17], v[188:189], 0, v[16:17]
	s_lshl_b32 s98, s98, 12
	s_add_i32 m0, s98, 0x24000
	s_nop 0
	global_load_lds_dwordx4 v[16:17], off
	global_load_lds_dwordx4 v[16:17], off offset:1024
	global_load_lds_dwordx4 v[16:17], off offset:2048
	global_load_lds_dwordx4 v[16:17], off offset:3072
.Lgu_ss_skip0:
	s_mov_b32 s33, s6
	s_barrier
	v_readlane_b32 s7, v254, 52
	s_branch .LBB0_1229

; #define GAS_ __attribute__((address_space(1)))
; __device__ __forceinline__ void rows_rstd(float (&rs)[2][4], const float* SS, int row0, int fq) {
;     f32x4 q[2][4];
; #pragma unroll
;     for (int ai = 0; ai < 2; ++ai)
; #pragma unroll
;         for (int m = 0; m < 4; ++m) q[ai][m] = *(const GAS_ f32x4*)(SS + (size_t)(row0 + ai * 128 + m * 16) * 16 + fq * 4);
; #pragma unroll
;     for (int ai = 0; ai < 2; ++ai)
; #pragma unroll
;         for (int m = 0; m < 4; ++m) { float s = (q[ai][m][0] + q[ai][m][1]) + (q[ai][m][2] + q[ai][m][3]); s += __shfl_xor(s, 16); s += __shfl_xor(s, 32);
;             rs[ai][m] = 1.0f / sqrtf(s * (1.0f / 1024.0f) + 1e-5f); }
;     __device__ __forceinline__ void operator()(const f32x4 (&acc)[2][2][4][2], const Unit& u, int wr, int wc, int fr, int fq) const {
;         const int row0 = u.pm * 256 + wr * 64 + fr, hc0 = u.pn * 128 + wc * 32 + 8 * fq;
;         float rsv[2][4];
;         rows_rstd(rsv, SS, row0, fq);
.LBB0_1235:
	v_and_b32_e32 v144, 64, v217
	v_lshlrev_b32_e32 v144, 7, v144
	v_lshl_add_u32 v144, v212, 4, v144
	v_add_u32_e32 v144, 0x24000, v144
	ds_read_b128 v[172:175], v144
	ds_read_b128 v[168:171], v144 offset:1024
	ds_read_b128 v[164:167], v144 offset:2048
	ds_read_b128 v[160:163], v144 offset:3072
	ds_read_b128 v[156:159], v144 offset:4096
	ds_read_b128 v[152:155], v144 offset:5120
	ds_read_b128 v[148:151], v144 offset:6144
	ds_read_b128 v[144:147], v144 offset:7168
	v_lshl_add_u32 v208, s33, 8, v217
	v_ashrrev_i32_e32 v209, 31, v208
	v_or_b32_e32 v206, 16, v208
	v_ashrrev_i32_e32 v207, 31, v206
	v_and_b32_e32 v179, 64, v212
	v_xor_b32_e32 v178, 16, v212
	v_add_u32_e32 v179, 64, v179
	v_cmp_lt_i32_e32 vcc, v178, v179
	v_xor_b32_e32 v180, 32, v212
	v_or_b32_e32 v204, 32, v208
	v_cndmask_b32_e32 v178, v212, v178, vcc
	v_cmp_lt_i32_e32 vcc, v180, v179
	v_ashrrev_i32_e32 v205, 31, v204
	v_cndmask_b32_e32 v179, v212, v180, vcc
	v_lshlrev_b32_e32 v178, 2, v178
	v_lshlrev_b32_e32 v179, 2, v179
	v_or_b32_e32 v202, 48, v208
	v_ashrrev_i32_e32 v203, 31, v202
	v_add_u32_e32 v200, 0x80, v208
	v_ashrrev_i32_e32 v201, 31, v200
	v_add_u32_e32 v198, 0x90, v208
	v_ashrrev_i32_e32 v199, 31, v198
	v_add_u32_e32 v196, 0xa0, v208
	v_ashrrev_i32_e32 v197, 31, v196
	v_add_u32_e32 v194, 0xb0, v208
	v_ashrrev_i32_e32 v195, 31, v194
	v_lshl_or_b32 v210, s2, 7, v219
	v_ashrrev_i32_e32 v211, 31, v210
	s_waitcnt lgkmcnt(0)
	v_mov_b32_e32 v180, v173
	v_mov_b32_e32 v181, v174
	v_mov_b32_e32 v173, v175
	v_pk_add_f32 v[172:173], v[180:181], v[172:173]
	s_nop 0
	v_add_f32_e32 v172, v172, v173
	ds_bpermute_b32 v173, v178, v172
	s_waitcnt lgkmcnt(0)
	v_add_f32_e32 v172, v172, v173
	ds_bpermute_b32 v173, v179, v172
	s_waitcnt lgkmcnt(0)
	v_add_f32_e32 v172, v172, v173
	v_fmamk_f32 v172, v172, 0x3a800000, v214
	v_cmp_gt_f32_e32 vcc, s68, v172
	v_mul_f32_e32 v173, 0x4f800000, v172
	s_nop 0
	v_cndmask_b32_e32 v172, v172, v173, vcc
	v_sqrt_f32_e32 v173, v172
	s_nop 0
	v_add_u32_e32 v174, -1, v173
	v_fma_f32 v175, -v174, v173, v172
	v_cmp_ge_f32_e64 s[8:9], 0, v175
	v_add_u32_e32 v175, 1, v173
	s_nop 0
	v_cndmask_b32_e64 v174, v173, v174, s[8:9]
	v_fma_f32 v173, -v175, v173, v172
	v_cmp_lt_f32_e64 s[8:9], 0, v173
	s_nop 1
	v_cndmask_b32_e64 v173, v174, v175, s[8:9]
	v_mul_f32_e32 v174, 0x37800000, v173
	v_cndmask_b32_e32 v173, v173, v174, vcc
	v_cmp_class_f32_e32 vcc, v172, v248
	s_nop 1
	v_cndmask_b32_e32 v172, v173, v172, vcc
	v_div_scale_f32 v173, s[0:1], v172, v172, 1.0
	v_rcp_f32_e32 v174, v173
	s_nop 0
	v_fma_f32 v175, -v173, v174, 1.0
	v_fmac_f32_e32 v174, v175, v174
	v_div_scale_f32 v175, vcc, 1.0, v172, 1.0
	v_mul_f32_e32 v180, v175, v174
	v_fma_f32 v181, -v173, v180, v175
	v_fmac_f32_e32 v180, v181, v174
	v_fma_f32 v173, -v173, v180, v175
	v_div_fmas_f32 v173, v173, v174, v180
	v_mov_b32_e32 v174, v169
	v_mov_b32_e32 v175, v170
	v_mov_b32_e32 v169, v171
	v_pk_add_f32 v[168:169], v[174:175], v[168:169]
	v_div_fixup_f32 v172, v173, v172, 1.0
	v_add_f32_e32 v168, v168, v169
	ds_bpermute_b32 v169, v178, v168
	s_waitcnt lgkmcnt(0)
	v_add_f32_e32 v168, v168, v169
	ds_bpermute_b32 v169, v179, v168
	s_waitcnt lgkmcnt(0)
	v_add_f32_e32 v168, v168, v169
	v_fmamk_f32 v168, v168, 0x3a800000, v214
	v_cmp_gt_f32_e32 vcc, s68, v168
	v_mul_f32_e32 v169, 0x4f800000, v168
	s_nop 0
	v_cndmask_b32_e32 v168, v168, v169, vcc
	v_sqrt_f32_e32 v169, v168
	s_nop 0
	v_add_u32_e32 v170, -1, v169
	v_fma_f32 v171, -v170, v169, v168
	v_cmp_ge_f32_e64 s[8:9], 0, v171
	v_add_u32_e32 v171, 1, v169
	s_nop 0
	v_cndmask_b32_e64 v170, v169, v170, s[8:9]
	v_fma_f32 v169, -v171, v169, v168
	v_cmp_lt_f32_e64 s[8:9], 0, v169
	s_nop 1
	v_cndmask_b32_e64 v169, v170, v171, s[8:9]
	v_mul_f32_e32 v170, 0x37800000, v169
	v_cndmask_b32_e32 v169, v169, v170, vcc
	v_cmp_class_f32_e32 vcc, v168, v248
	s_nop 1
	v_cndmask_b32_e32 v168, v169, v168, vcc
	v_div_scale_f32 v169, s[0:1], v168, v168, 1.0
	v_rcp_f32_e32 v170, v169
	s_nop 0
	v_fma_f32 v171, -v169, v170, 1.0
	v_fmac_f32_e32 v170, v171, v170
	v_div_scale_f32 v171, vcc, 1.0, v168, 1.0
	v_mul_f32_e32 v173, v171, v170
	v_fma_f32 v174, -v169, v173, v171
	v_fmac_f32_e32 v173, v174, v170
	v_fma_f32 v169, -v169, v173, v171
	v_div_fmas_f32 v169, v169, v170, v173
	v_mov_b32_e32 v170, v165
	v_mov_b32_e32 v171, v166
	v_mov_b32_e32 v165, v167
	v_pk_add_f32 v[164:165], v[170:171], v[164:165]
	v_div_fixup_f32 v168, v169, v168, 1.0
	v_add_f32_e32 v164, v164, v165
	ds_bpermute_b32 v165, v178, v164
	v_pk_mul_f32 v[140:141], v[140:141], v[172:173] op_sel_hi:[1,0]
	v_pk_mul_f32 v[132:133], v[132:133], v[172:173] op_sel_hi:[1,0]
	v_pk_mul_f32 v[142:143], v[142:143], v[172:173] op_sel_hi:[1,0]
	v_pk_mul_f32 v[134:135], v[134:135], v[172:173] op_sel_hi:[1,0]
	s_waitcnt lgkmcnt(0)
	v_add_f32_e32 v164, v164, v165
	ds_bpermute_b32 v165, v179, v164
	v_pk_mul_f32 v[136:137], v[136:137], v[172:173] op_sel_hi:[1,0]
	v_pk_mul_f32 v[138:139], v[138:139], v[172:173] op_sel_hi:[1,0]
	s_waitcnt lgkmcnt(0)
; __device__ __forceinline__ void rows_rstd(float (&rs)[2][4], const float* SS, int row0, int fq) {
;     ...
;         for (int m = 0; m < 4; ++m) { float s = (q[ai][m][0] + q[ai][m][1]) + (q[ai][m][2] + q[ai][m][3]); s += __shfl_xor(s, 16); s += __shfl_xor(s, 32);
;             rs[ai][m] = 1.0f / sqrtf(s * (1.0f / 1024.0f) + 1e-5f); }
;     __device__ __forceinline__ void operator()(const f32x4 (&acc)[2][2][4][2], const Unit& u, int wr, int wc, int fr, int fq) const {
;     ...
;                 const f32x4 g0 = acc[ai][0][m][0] * rs, g1 = acc[ai][0][m][1] * rs, u0 = acc[ai][1][m][0] * rs, u1 = acc[ai][1][m][1] * rs;
	v_add_f32_e32 v164, v164, v165
	v_fmamk_f32 v164, v164, 0x3a800000, v214
	v_cmp_gt_f32_e32 vcc, s68, v164
	v_mul_f32_e32 v165, 0x4f800000, v164
	s_nop 0
	v_cndmask_b32_e32 v164, v164, v165, vcc
	v_sqrt_f32_e32 v165, v164
	s_nop 0
	v_add_u32_e32 v166, -1, v165
	v_fma_f32 v167, -v166, v165, v164
	v_cmp_ge_f32_e64 s[8:9], 0, v167
	v_add_u32_e32 v167, 1, v165
	s_nop 0
	v_cndmask_b32_e64 v166, v165, v166, s[8:9]
	v_fma_f32 v165, -v167, v165, v164
	v_cmp_lt_f32_e64 s[8:9], 0, v165
	s_nop 1
	v_cndmask_b32_e64 v165, v166, v167, s[8:9]
	v_mul_f32_e32 v166, 0x37800000, v165
	v_cndmask_b32_e32 v165, v165, v166, vcc
	v_cmp_class_f32_e32 vcc, v164, v248
	s_nop 1
	v_cndmask_b32_e32 v164, v165, v164, vcc
	v_div_scale_f32 v165, s[0:1], v164, v164, 1.0
	v_rcp_f32_e32 v166, v165
	s_nop 0
	v_fma_f32 v167, -v165, v166, 1.0
	v_fmac_f32_e32 v166, v167, v166
	v_div_scale_f32 v167, vcc, 1.0, v164, 1.0
	v_mul_f32_e32 v169, v167, v166
	v_fma_f32 v170, -v165, v169, v167
	v_fmac_f32_e32 v169, v170, v166
	v_fma_f32 v165, -v165, v169, v167
	v_div_fmas_f32 v165, v165, v166, v169
	v_mov_b32_e32 v166, v161
	v_mov_b32_e32 v167, v162
	v_mov_b32_e32 v161, v163
	v_pk_add_f32 v[160:161], v[166:167], v[160:161]
	v_div_fixup_f32 v164, v165, v164, 1.0
	v_add_f32_e32 v160, v160, v161
	ds_bpermute_b32 v161, v178, v160
	v_pk_mul_f32 v[124:125], v[124:125], v[168:169] op_sel_hi:[1,0]
	v_pk_mul_f32 v[116:117], v[116:117], v[168:169] op_sel_hi:[1,0]
	v_pk_mul_f32 v[126:127], v[126:127], v[168:169] op_sel_hi:[1,0]
	v_pk_mul_f32 v[118:119], v[118:119], v[168:169] op_sel_hi:[1,0]
	s_waitcnt lgkmcnt(0)
	v_add_f32_e32 v160, v160, v161
	ds_bpermute_b32 v161, v179, v160
	v_pk_mul_f32 v[120:121], v[120:121], v[168:169] op_sel_hi:[1,0]
	v_pk_mul_f32 v[122:123], v[122:123], v[168:169] op_sel_hi:[1,0]
	s_waitcnt lgkmcnt(0)
	v_add_f32_e32 v160, v160, v161
	v_fmamk_f32 v160, v160, 0x3a800000, v214
	v_cmp_gt_f32_e32 vcc, s68, v160
	v_mul_f32_e32 v161, 0x4f800000, v160
	s_nop 0
	v_cndmask_b32_e32 v160, v160, v161, vcc
	v_sqrt_f32_e32 v161, v160
	s_nop 0
	v_add_u32_e32 v162, -1, v161
	v_fma_f32 v163, -v162, v161, v160
	v_cmp_ge_f32_e64 s[8:9], 0, v163
	v_add_u32_e32 v163, 1, v161
	s_nop 0
	v_cndmask_b32_e64 v162, v161, v162, s[8:9]
	v_fma_f32 v161, -v163, v161, v160
	v_cmp_lt_f32_e64 s[8:9], 0, v161
	s_nop 1
	v_cndmask_b32_e64 v161, v162, v163, s[8:9]
	v_mul_f32_e32 v162, 0x37800000, v161
	v_cndmask_b32_e32 v161, v161, v162, vcc
	v_cmp_class_f32_e32 vcc, v160, v248
	s_nop 1
	v_cndmask_b32_e32 v160, v161, v160, vcc
	v_div_scale_f32 v161, s[0:1], v160, v160, 1.0
	v_rcp_f32_e32 v162, v161
	s_nop 0
	v_fma_f32 v163, -v161, v162, 1.0
	v_fmac_f32_e32 v162, v163, v162
	v_div_scale_f32 v163, vcc, 1.0, v160, 1.0
	v_mul_f32_e32 v165, v163, v162
	v_fma_f32 v166, -v161, v165, v163
	v_fmac_f32_e32 v165, v166, v162
	v_fma_f32 v161, -v161, v165, v163
	v_div_fmas_f32 v161, v161, v162, v165
	v_mov_b32_e32 v162, v157
	v_mov_b32_e32 v163, v158
	v_mov_b32_e32 v157, v159
	v_pk_add_f32 v[156:157], v[162:163], v[156:157]
	v_div_fixup_f32 v160, v161, v160, 1.0
	v_add_f32_e32 v156, v156, v157
	ds_bpermute_b32 v157, v178, v156
	v_pk_mul_f32 v[108:109], v[108:109], v[164:165] op_sel_hi:[1,0]
	v_pk_mul_f32 v[100:101], v[100:101], v[164:165] op_sel_hi:[1,0]
	v_pk_mul_f32 v[110:111], v[110:111], v[164:165] op_sel_hi:[1,0]
	v_pk_mul_f32 v[102:103], v[102:103], v[164:165] op_sel_hi:[1,0]
	s_waitcnt lgkmcnt(0)
	v_add_f32_e32 v156, v156, v157
	ds_bpermute_b32 v157, v179, v156
	v_pk_mul_f32 v[104:105], v[104:105], v[164:165] op_sel_hi:[1,0]
	v_pk_mul_f32 v[106:107], v[106:107], v[164:165] op_sel_hi:[1,0]
	s_waitcnt lgkmcnt(0)
	v_add_f32_e32 v156, v156, v157
	v_fmamk_f32 v156, v156, 0x3a800000, v214
	v_cmp_gt_f32_e32 vcc, s68, v156
	v_mul_f32_e32 v157, 0x4f800000, v156
	s_nop 0
	v_cndmask_b32_e32 v156, v156, v157, vcc
	v_sqrt_f32_e32 v157, v156
	s_nop 0
	v_add_u32_e32 v158, -1, v157
	v_fma_f32 v159, -v158, v157, v156
	v_cmp_ge_f32_e64 s[8:9], 0, v159
	v_add_u32_e32 v159, 1, v157
	s_nop 0
	v_cndmask_b32_e64 v158, v157, v158, s[8:9]
	v_fma_f32 v157, -v159, v157, v156
	v_cmp_lt_f32_e64 s[8:9], 0, v157
	s_nop 1
	v_cndmask_b32_e64 v157, v158, v159, s[8:9]
	v_mul_f32_e32 v158, 0x37800000, v157
	v_cndmask_b32_e32 v157, v157, v158, vcc
	v_cmp_class_f32_e32 vcc, v156, v248
	s_nop 1
	v_cndmask_b32_e32 v156, v157, v156, vcc
	v_div_scale_f32 v157, s[0:1], v156, v156, 1.0
	v_rcp_f32_e32 v158, v157
	s_nop 0
	v_fma_f32 v159, -v157, v158, 1.0
	v_fmac_f32_e32 v158, v159, v158
	v_div_scale_f32 v159, vcc, 1.0, v156, 1.0
	v_mul_f32_e32 v161, v159, v158
	v_fma_f32 v162, -v157, v161, v159
	v_fmac_f32_e32 v161, v162, v158
	v_fma_f32 v157, -v157, v161, v159
	v_div_fmas_f32 v157, v157, v158, v161
	v_mov_b32_e32 v158, v153
	v_mov_b32_e32 v159, v154
	v_mov_b32_e32 v153, v155
	v_pk_add_f32 v[152:153], v[158:159], v[152:153]
	v_div_fixup_f32 v156, v157, v156, 1.0
	v_add_f32_e32 v152, v152, v153
	ds_bpermute_b32 v153, v178, v152
	v_pk_mul_f32 v[92:93], v[92:93], v[160:161] op_sel_hi:[1,0]
	v_pk_mul_f32 v[84:85], v[84:85], v[160:161] op_sel_hi:[1,0]
	v_pk_mul_f32 v[94:95], v[94:95], v[160:161] op_sel_hi:[1,0]
	v_pk_mul_f32 v[86:87], v[86:87], v[160:161] op_sel_hi:[1,0]
	s_waitcnt lgkmcnt(0)
	v_add_f32_e32 v152, v152, v153
	ds_bpermute_b32 v153, v179, v152
	v_pk_mul_f32 v[88:89], v[88:89], v[160:161] op_sel_hi:[1,0]
	v_pk_mul_f32 v[90:91], v[90:91], v[160:161] op_sel_hi:[1,0]
	s_waitcnt lgkmcnt(0)
; __device__ __forceinline__ unsigned pk2(float lo, float hi) { f32x2_t v = {lo, hi}; bf16x2_t b = __builtin_convertvector(v, bf16x2_t); return __builtin_bit_cast(unsigned, b); }
; __device__ __forceinline__ float silu_f(float g) { return g * __builtin_amdgcn_rcpf(1.0f + __expf(-g)); }
; __device__ __forceinline__ void rows_rstd(float (&rs)[2][4], const float* SS, int row0, int fq) {
;     ...
;         for (int m = 0; m < 4; ++m) { float s = (q[ai][m][0] + q[ai][m][1]) + (q[ai][m][2] + q[ai][m][3]); s += __shfl_xor(s, 16); s += __shfl_xor(s, 32);
;             rs[ai][m] = 1.0f / sqrtf(s * (1.0f / 1024.0f) + 1e-5f); }
;     __device__ __forceinline__ void operator()(const f32x4 (&acc)[2][2][4][2], const Unit& u, int wr, int wc, int fr, int fq) const {
;     ...
;                 const f32x4 g0 = acc[ai][0][m][0] * rs, g1 = acc[ai][0][m][1] * rs, u0 = acc[ai][1][m][0] * rs, u1 = acc[ai][1][m][1] * rs;
;                 u32x4 w; w.x = pk2(silu_f(g0[0]) * u0[0], silu_f(g0[1]) * u0[1]); w.y = pk2(silu_f(g0[2]) * u0[2], silu_f(g0[3]) * u0[3]);
;                 w.z = pk2(silu_f(g1[0]) * u1[0], silu_f(g1[1]) * u1[1]); w.w = pk2(silu_f(g1[2]) * u1[2], silu_f(g1[3]) * u1[3]);
	v_add_f32_e32 v152, v152, v153
	v_fmamk_f32 v152, v152, 0x3a800000, v214
	v_cmp_gt_f32_e32 vcc, s68, v152
	v_mul_f32_e32 v153, 0x4f800000, v152
	s_nop 0
	v_cndmask_b32_e32 v152, v152, v153, vcc
	v_sqrt_f32_e32 v153, v152
	s_nop 0
	v_add_u32_e32 v154, -1, v153
	v_fma_f32 v155, -v154, v153, v152
	v_cmp_ge_f32_e64 s[8:9], 0, v155
	v_add_u32_e32 v155, 1, v153
	s_nop 0
	v_cndmask_b32_e64 v154, v153, v154, s[8:9]
	v_fma_f32 v153, -v155, v153, v152
	v_cmp_lt_f32_e64 s[8:9], 0, v153
	s_nop 1
	v_cndmask_b32_e64 v153, v154, v155, s[8:9]
	v_mul_f32_e32 v154, 0x37800000, v153
	v_cndmask_b32_e32 v153, v153, v154, vcc
	v_cmp_class_f32_e32 vcc, v152, v248
	s_nop 1
	v_cndmask_b32_e32 v152, v153, v152, vcc
	v_div_scale_f32 v153, s[0:1], v152, v152, 1.0
	v_rcp_f32_e32 v154, v153
	s_nop 0
	v_fma_f32 v155, -v153, v154, 1.0
	v_fmac_f32_e32 v154, v155, v154
	v_div_scale_f32 v155, vcc, 1.0, v152, 1.0
	v_mul_f32_e32 v157, v155, v154
	v_fma_f32 v158, -v153, v157, v155
	v_fmac_f32_e32 v157, v158, v154
	v_fma_f32 v153, -v153, v157, v155
	v_div_fmas_f32 v153, v153, v154, v157
	v_mov_b32_e32 v154, v149
	v_mov_b32_e32 v155, v150
	v_mov_b32_e32 v149, v151
	v_pk_add_f32 v[148:149], v[154:155], v[148:149]
	v_pk_mul_f32 v[158:159], v[130:131], v[172:173] op_sel_hi:[1,0]
	v_add_f32_e32 v148, v148, v149
	ds_bpermute_b32 v149, v178, v148
	v_pk_mul_f32 v[130:131], v[128:129], v[172:173] op_sel_hi:[1,0]
	v_mul_f32_e32 v128, 0xbfb8aa3b, v140
	v_mul_f32_e32 v129, 0xbfb8aa3b, v141
	v_exp_f32_e32 v128, v128
	s_waitcnt lgkmcnt(0)
	v_add_f32_e32 v148, v148, v149
	ds_bpermute_b32 v149, v179, v148
	v_exp_f32_e32 v129, v129
	v_add_f32_e32 v128, 1.0, v128
	v_rcp_f32_e32 v128, v128
	v_div_fixup_f32 v152, v153, v152, 1.0
	s_waitcnt lgkmcnt(0)
	v_add_f32_e32 v148, v148, v149
	v_fmamk_f32 v148, v148, 0x3a800000, v214
	v_cmp_gt_f32_e32 vcc, s68, v148
	v_mul_f32_e32 v149, 0x4f800000, v148
	v_add_f32_e32 v129, 1.0, v129
	v_cndmask_b32_e32 v148, v148, v149, vcc
	v_sqrt_f32_e32 v149, v148
	v_rcp_f32_e32 v129, v129
	v_pk_mul_f32 v[76:77], v[76:77], v[156:157] op_sel_hi:[1,0]
	v_pk_mul_f32 v[68:69], v[68:69], v[156:157] op_sel_hi:[1,0]
	v_add_u32_e32 v150, -1, v149
	v_fma_f32 v151, -v150, v149, v148
	v_cmp_ge_f32_e64 s[8:9], 0, v151
	v_add_u32_e32 v151, 1, v149
	v_pk_mul_f32 v[128:129], v[140:141], v[128:129]
	v_cndmask_b32_e64 v150, v149, v150, s[8:9]
	v_fma_f32 v149, -v151, v149, v148
	v_cmp_lt_f32_e64 s[8:9], 0, v149
	v_pk_mul_f32 v[128:129], v[132:133], v[128:129]
	v_pk_mul_f32 v[78:79], v[78:79], v[156:157] op_sel_hi:[1,0]
	v_cndmask_b32_e64 v149, v150, v151, s[8:9]
	v_mul_f32_e32 v150, 0x37800000, v149
	v_cndmask_b32_e32 v149, v149, v150, vcc
	v_cmp_class_f32_e32 vcc, v148, v248
	v_cvt_pk_bf16_f32 v128, v128, v129
	v_mul_f32_e32 v129, 0xbfb8aa3b, v142
	v_cndmask_b32_e32 v148, v149, v148, vcc
	v_div_scale_f32 v149, s[0:1], v148, v148, 1.0
	v_rcp_f32_e32 v150, v149
	v_exp_f32_e32 v129, v129
	v_pk_mul_f32 v[70:71], v[70:71], v[156:157] op_sel_hi:[1,0]
	v_pk_mul_f32 v[72:73], v[72:73], v[156:157] op_sel_hi:[1,0]
	v_fma_f32 v151, -v149, v150, 1.0
	v_fmac_f32_e32 v150, v151, v150
	v_div_scale_f32 v151, vcc, 1.0, v148, 1.0
	v_mul_f32_e32 v153, v151, v150
	v_fma_f32 v154, -v149, v153, v151
	v_fmac_f32_e32 v153, v154, v150
	v_fma_f32 v149, -v149, v153, v151
	v_div_fmas_f32 v149, v149, v150, v153
	v_div_fixup_f32 v150, v149, v148, 1.0
	v_mov_b32_e32 v148, v145
	v_mov_b32_e32 v149, v146
	v_mov_b32_e32 v145, v147
	v_pk_add_f32 v[144:145], v[148:149], v[144:145]
	v_add_f32_e32 v129, 1.0, v129
	v_add_f32_e32 v144, v144, v145
	v_rcp_f32_e32 v132, v129
	v_mul_f32_e32 v129, 0xbfb8aa3b, v143
	ds_bpermute_b32 v145, v178, v144
	v_exp_f32_e32 v129, v129
	v_pk_mul_f32 v[74:75], v[74:75], v[156:157] op_sel_hi:[1,0]
	v_pk_mul_f32 v[60:61], v[60:61], v[152:153] op_sel_hi:[1,0]
	v_pk_mul_f32 v[52:53], v[52:53], v[152:153] op_sel_hi:[1,0]
	v_add_f32_e32 v129, 1.0, v129
	s_waitcnt lgkmcnt(0)
	v_add_f32_e32 v144, v144, v145
	v_rcp_f32_e32 v133, v129
	ds_bpermute_b32 v145, v179, v144
	v_pk_mul_f32 v[62:63], v[62:63], v[152:153] op_sel_hi:[1,0]
	v_pk_mul_f32 v[54:55], v[54:55], v[152:153] op_sel_hi:[1,0]
	v_pk_mul_f32 v[132:133], v[142:143], v[132:133]
	v_pk_mul_f32 v[56:57], v[56:57], v[152:153] op_sel_hi:[1,0]
	v_pk_mul_f32 v[132:133], v[134:135], v[132:133]
	s_waitcnt lgkmcnt(0)
; #define GAS_ __attribute__((address_space(1)))
; __device__ __forceinline__ unsigned pk2(float lo, float hi) { f32x2_t v = {lo, hi}; bf16x2_t b = __builtin_convertvector(v, bf16x2_t); return __builtin_bit_cast(unsigned, b); }
; __device__ __forceinline__ float silu_f(float g) { return g * __builtin_amdgcn_rcpf(1.0f + __expf(-g)); }
;     __device__ __forceinline__ void operator()(const f32x4 (&acc)[2][2][4][2], const Unit& u, int wr, int wc, int fr, int fq) const {
;     ...
;                 bf16_t* rowp = H + (size_t)(row0 + ai * 128 + m * 16) * ldh + hc0;
;                 const float rs = rsv[ai][m];
;                 const f32x4 g0 = acc[ai][0][m][0] * rs, g1 = acc[ai][0][m][1] * rs, u0 = acc[ai][1][m][0] * rs, u1 = acc[ai][1][m][1] * rs;
;                 u32x4 w; w.x = pk2(silu_f(g0[0]) * u0[0], silu_f(g0[1]) * u0[1]); w.y = pk2(silu_f(g0[2]) * u0[2], silu_f(g0[3]) * u0[3]);
;                 w.z = pk2(silu_f(g1[0]) * u1[0], silu_f(g1[1]) * u1[1]); w.w = pk2(silu_f(g1[2]) * u1[2], silu_f(g1[3]) * u1[3]);
;                 *(GAS_ u32x4*)rowp = w;
;                 asm volatile("" ::: "memory");
;             }
	v_add_f32_e32 v144, v144, v145
	v_cvt_pk_bf16_f32 v129, v132, v133
	v_mul_f32_e32 v132, 0xbfb8aa3b, v136
	v_mul_f32_e32 v133, 0xbfb8aa3b, v137
	v_fmamk_f32 v144, v144, 0x3a800000, v214
	v_exp_f32_e32 v132, v132
	v_exp_f32_e32 v133, v133
	v_cmp_gt_f32_e32 vcc, s68, v144
	v_mul_f32_e32 v145, 0x4f800000, v144
	v_add_f32_e32 v132, 1.0, v132
	v_cndmask_b32_e32 v144, v144, v145, vcc
	v_sqrt_f32_e32 v145, v144
	v_add_f32_e32 v133, 1.0, v133
	v_rcp_f32_e32 v132, v132
	v_rcp_f32_e32 v133, v133
	v_add_u32_e32 v146, -1, v145
	v_fma_f32 v147, -v146, v145, v144
	v_cmp_ge_f32_e64 s[8:9], 0, v147
	v_add_u32_e32 v147, 1, v145
	v_pk_mul_f32 v[132:133], v[136:137], v[132:133]
	v_cndmask_b32_e64 v146, v145, v146, s[8:9]
	v_fma_f32 v145, -v147, v145, v144
	v_pk_mul_f32 v[130:131], v[130:131], v[132:133]
	v_cmp_lt_f32_e64 s[8:9], 0, v145
	v_cvt_pk_bf16_f32 v130, v130, v131
	v_mul_f32_e32 v131, 0xbfb8aa3b, v138
	v_cndmask_b32_e64 v145, v146, v147, s[8:9]
	v_exp_f32_e32 v131, v131
	v_mul_f32_e32 v146, 0x37800000, v145
	v_cndmask_b32_e32 v145, v145, v146, vcc
	v_cmp_class_f32_e32 vcc, v144, v248
	v_add_f32_e32 v131, 1.0, v131
	v_rcp_f32_e32 v132, v131
	v_cndmask_b32_e32 v144, v145, v144, vcc
	v_div_scale_f32 v145, s[0:1], v144, v144, 1.0
	v_rcp_f32_e32 v146, v145
	v_mul_f32_e32 v131, 0xbfb8aa3b, v139
	v_exp_f32_e32 v131, v131
	v_pk_mul_f32 v[58:59], v[58:59], v[152:153] op_sel_hi:[1,0]
	v_fma_f32 v147, -v145, v146, 1.0
	v_fmac_f32_e32 v146, v147, v146
	v_div_scale_f32 v147, vcc, 1.0, v144, 1.0
	v_add_f32_e32 v131, 1.0, v131
	v_mul_f32_e32 v148, v147, v146
	v_rcp_f32_e32 v133, v131
	v_fma_f32 v149, -v145, v148, v147
	v_fmac_f32_e32 v148, v149, v146
	v_fma_f32 v145, -v145, v148, v147
	v_div_fmas_f32 v145, v145, v146, v148
	v_mov_b64_e32 v[146:147], s[12:13]
	v_pk_mul_f32 v[132:133], v[138:139], v[132:133]
	v_mad_i64_i32 v[154:155], s[0:1], v208, s62, v[146:147]
	v_lshlrev_b64 v[148:149], 1, v[210:211]
	v_pk_mul_f32 v[132:133], v[158:159], v[132:133]
	v_lshl_add_u64 v[154:155], v[154:155], 0, v[148:149]
	v_cvt_pk_bf16_f32 v131, v132, v133
	global_store_dwordx4 v[154:155], v[128:131], off
	v_pk_mul_f32 v[44:45], v[44:45], v[150:151] op_sel_hi:[1,0]
	v_pk_mul_f32 v[36:37], v[36:37], v[150:151] op_sel_hi:[1,0]
	v_pk_mul_f32 v[130:131], v[114:115], v[168:169] op_sel_hi:[1,0]
	v_pk_mul_f32 v[114:115], v[112:113], v[168:169] op_sel_hi:[1,0]
	v_mul_f32_e32 v112, 0xbfb8aa3b, v124
	v_mul_f32_e32 v113, 0xbfb8aa3b, v125
	v_exp_f32_e32 v112, v112
	v_exp_f32_e32 v113, v113
	v_mad_i64_i32 v[128:129], s[0:1], v206, s62, v[146:147]
	v_add_f32_e32 v112, 1.0, v112
	v_add_f32_e32 v113, 1.0, v113
	v_rcp_f32_e32 v112, v112
	v_rcp_f32_e32 v113, v113
	v_lshl_add_u64 v[128:129], v[128:129], 0, v[148:149]
	v_pk_mul_f32 v[46:47], v[46:47], v[150:151] op_sel_hi:[1,0]
	v_pk_mul_f32 v[38:39], v[38:39], v[150:151] op_sel_hi:[1,0]
	v_pk_mul_f32 v[112:113], v[124:125], v[112:113]
	v_pk_mul_f32 v[40:41], v[40:41], v[150:151] op_sel_hi:[1,0]
	v_pk_mul_f32 v[112:113], v[116:117], v[112:113]
	v_pk_mul_f32 v[42:43], v[42:43], v[150:151] op_sel_hi:[1,0]
	v_cvt_pk_bf16_f32 v112, v112, v113
	v_mul_f32_e32 v113, 0xbfb8aa3b, v126
	v_exp_f32_e32 v113, v113
	v_div_fixup_f32 v144, v145, v144, 1.0
	v_pk_mul_f32 v[28:29], v[28:29], v[144:145] op_sel_hi:[1,0]
	v_pk_mul_f32 v[20:21], v[20:21], v[144:145] op_sel_hi:[1,0]
	v_add_f32_e32 v113, 1.0, v113
	v_rcp_f32_e32 v116, v113
	v_mul_f32_e32 v113, 0xbfb8aa3b, v127
	v_exp_f32_e32 v113, v113
	v_pk_mul_f32 v[30:31], v[30:31], v[144:145] op_sel_hi:[1,0]
	v_pk_mul_f32 v[22:23], v[22:23], v[144:145] op_sel_hi:[1,0]
	v_pk_mul_f32 v[24:25], v[24:25], v[144:145] op_sel_hi:[1,0]
	v_add_f32_e32 v113, 1.0, v113
	v_rcp_f32_e32 v117, v113
	v_pk_mul_f32 v[26:27], v[26:27], v[144:145] op_sel_hi:[1,0]
	s_andn2_b64 vcc, exec, s[6:7]
	v_pk_mul_f32 v[116:117], v[126:127], v[116:117]
	s_nop 0
	v_pk_mul_f32 v[116:117], v[118:119], v[116:117]
	s_nop 0
	v_cvt_pk_bf16_f32 v113, v116, v117
	v_mul_f32_e32 v116, 0xbfb8aa3b, v120
	v_mul_f32_e32 v117, 0xbfb8aa3b, v121
	v_exp_f32_e32 v116, v116
	v_exp_f32_e32 v117, v117
	v_add_f32_e32 v116, 1.0, v116
	v_add_f32_e32 v117, 1.0, v117
	v_rcp_f32_e32 v116, v116
	v_rcp_f32_e32 v117, v117
	s_nop 0
	v_pk_mul_f32 v[116:117], v[120:121], v[116:117]
	s_nop 0
	v_pk_mul_f32 v[114:115], v[114:115], v[116:117]
	s_nop 0
	v_cvt_pk_bf16_f32 v114, v114, v115
	v_mul_f32_e32 v115, 0xbfb8aa3b, v122
	v_exp_f32_e32 v115, v115
	s_nop 0
	v_add_f32_e32 v115, 1.0, v115
	v_rcp_f32_e32 v116, v115
	v_mul_f32_e32 v115, 0xbfb8aa3b, v123
	v_exp_f32_e32 v115, v115
	s_nop 0
	v_add_f32_e32 v115, 1.0, v115
	v_rcp_f32_e32 v117, v115
	s_nop 0
	v_pk_mul_f32 v[116:117], v[122:123], v[116:117]
	s_nop 0
	v_pk_mul_f32 v[116:117], v[130:131], v[116:117]
	s_nop 0
	v_cvt_pk_bf16_f32 v115, v116, v117
	global_store_dwordx4 v[128:129], v[112:115], off
	s_nop 1
	v_pk_mul_f32 v[114:115], v[98:99], v[164:165] op_sel_hi:[1,0]
	v_pk_mul_f32 v[98:99], v[96:97], v[164:165] op_sel_hi:[1,0]
	v_mul_f32_e32 v96, 0xbfb8aa3b, v108
	v_mul_f32_e32 v97, 0xbfb8aa3b, v109
	v_exp_f32_e32 v96, v96
	v_exp_f32_e32 v97, v97
	v_mad_i64_i32 v[112:113], s[0:1], v204, s62, v[146:147]
	v_add_f32_e32 v96, 1.0, v96
	v_add_f32_e32 v97, 1.0, v97
	v_rcp_f32_e32 v96, v96
	v_rcp_f32_e32 v97, v97
	v_lshl_add_u64 v[112:113], v[112:113], 0, v[148:149]
	v_pk_mul_f32 v[96:97], v[108:109], v[96:97]
	s_nop 0
	v_pk_mul_f32 v[96:97], v[100:101], v[96:97]
	s_nop 0
	v_cvt_pk_bf16_f32 v96, v96, v97
	v_mul_f32_e32 v97, 0xbfb8aa3b, v110
	v_exp_f32_e32 v97, v97
	s_nop 0
	v_add_f32_e32 v97, 1.0, v97
	v_rcp_f32_e32 v100, v97
	v_mul_f32_e32 v97, 0xbfb8aa3b, v111
	v_exp_f32_e32 v97, v97
	s_nop 0
	v_add_f32_e32 v97, 1.0, v97
	v_rcp_f32_e32 v101, v97
; #define GAS_ __attribute__((address_space(1)))
; __device__ __forceinline__ unsigned pk2(float lo, float hi) { f32x2_t v = {lo, hi}; bf16x2_t b = __builtin_convertvector(v, bf16x2_t); return __builtin_bit_cast(unsigned, b); }
; __device__ __forceinline__ float silu_f(float g) { return g * __builtin_amdgcn_rcpf(1.0f + __expf(-g)); }
;     __device__ __forceinline__ void operator()(const f32x4 (&acc)[2][2][4][2], const Unit& u, int wr, int wc, int fr, int fq) const {
;     ...
;                 bf16_t* rowp = H + (size_t)(row0 + ai * 128 + m * 16) * ldh + hc0;
;                 const float rs = rsv[ai][m];
;                 const f32x4 g0 = acc[ai][0][m][0] * rs, g1 = acc[ai][0][m][1] * rs, u0 = acc[ai][1][m][0] * rs, u1 = acc[ai][1][m][1] * rs;
;                 u32x4 w; w.x = pk2(silu_f(g0[0]) * u0[0], silu_f(g0[1]) * u0[1]); w.y = pk2(silu_f(g0[2]) * u0[2], silu_f(g0[3]) * u0[3]);
;                 w.z = pk2(silu_f(g1[0]) * u1[0], silu_f(g1[1]) * u1[1]); w.w = pk2(silu_f(g1[2]) * u1[2], silu_f(g1[3]) * u1[3]);
;                 *(GAS_ u32x4*)rowp = w;
;                 asm volatile("" ::: "memory");
;             }
	s_nop 0
	v_pk_mul_f32 v[100:101], v[110:111], v[100:101]
	s_nop 0
	v_pk_mul_f32 v[100:101], v[102:103], v[100:101]
	s_nop 0
	v_cvt_pk_bf16_f32 v97, v100, v101
	v_mul_f32_e32 v100, 0xbfb8aa3b, v104
	v_mul_f32_e32 v101, 0xbfb8aa3b, v105
	v_exp_f32_e32 v100, v100
	v_exp_f32_e32 v101, v101
	v_add_f32_e32 v100, 1.0, v100
	v_add_f32_e32 v101, 1.0, v101
	v_rcp_f32_e32 v100, v100
	v_rcp_f32_e32 v101, v101
	s_nop 0
	v_pk_mul_f32 v[100:101], v[104:105], v[100:101]
	s_nop 0
	v_pk_mul_f32 v[98:99], v[98:99], v[100:101]
	s_nop 0
	v_cvt_pk_bf16_f32 v98, v98, v99
	v_mul_f32_e32 v99, 0xbfb8aa3b, v106
	v_exp_f32_e32 v99, v99
	s_nop 0
	v_add_f32_e32 v99, 1.0, v99
	v_rcp_f32_e32 v100, v99
	v_mul_f32_e32 v99, 0xbfb8aa3b, v107
	v_exp_f32_e32 v99, v99
	s_nop 0
	v_add_f32_e32 v99, 1.0, v99
	v_rcp_f32_e32 v101, v99
	s_nop 0
	v_pk_mul_f32 v[100:101], v[106:107], v[100:101]
	s_nop 0
	v_pk_mul_f32 v[100:101], v[114:115], v[100:101]
	s_nop 0
	v_cvt_pk_bf16_f32 v99, v100, v101
	global_store_dwordx4 v[112:113], v[96:99], off
	s_nop 1
	v_pk_mul_f32 v[98:99], v[82:83], v[160:161] op_sel_hi:[1,0]
	v_pk_mul_f32 v[82:83], v[80:81], v[160:161] op_sel_hi:[1,0]
	v_mul_f32_e32 v80, 0xbfb8aa3b, v92
	v_mul_f32_e32 v81, 0xbfb8aa3b, v93
	v_exp_f32_e32 v80, v80
	v_exp_f32_e32 v81, v81
	v_mad_i64_i32 v[96:97], s[0:1], v202, s62, v[146:147]
	v_add_f32_e32 v80, 1.0, v80
	v_add_f32_e32 v81, 1.0, v81
	v_rcp_f32_e32 v80, v80
	v_rcp_f32_e32 v81, v81
	v_lshl_add_u64 v[96:97], v[96:97], 0, v[148:149]
	v_pk_mul_f32 v[80:81], v[92:93], v[80:81]
	s_nop 0
	v_pk_mul_f32 v[80:81], v[84:85], v[80:81]
	s_nop 0
	v_cvt_pk_bf16_f32 v80, v80, v81
	v_mul_f32_e32 v81, 0xbfb8aa3b, v94
	v_exp_f32_e32 v81, v81
	s_nop 0
	v_add_f32_e32 v81, 1.0, v81
	v_rcp_f32_e32 v84, v81
	v_mul_f32_e32 v81, 0xbfb8aa3b, v95
	v_exp_f32_e32 v81, v81
	s_nop 0
	v_add_f32_e32 v81, 1.0, v81
	v_rcp_f32_e32 v85, v81
	s_nop 0
	v_pk_mul_f32 v[84:85], v[94:95], v[84:85]
	s_nop 0
	v_pk_mul_f32 v[84:85], v[86:87], v[84:85]
	s_nop 0
	v_cvt_pk_bf16_f32 v81, v84, v85
	v_mul_f32_e32 v84, 0xbfb8aa3b, v88
	v_mul_f32_e32 v85, 0xbfb8aa3b, v89
	v_exp_f32_e32 v84, v84
	v_exp_f32_e32 v85, v85
	v_add_f32_e32 v84, 1.0, v84
	v_add_f32_e32 v85, 1.0, v85
	v_rcp_f32_e32 v84, v84
	v_rcp_f32_e32 v85, v85
	s_nop 0
	v_pk_mul_f32 v[84:85], v[88:89], v[84:85]
	s_nop 0
	v_pk_mul_f32 v[82:83], v[82:83], v[84:85]
	s_nop 0
	v_cvt_pk_bf16_f32 v82, v82, v83
	v_mul_f32_e32 v83, 0xbfb8aa3b, v90
	v_exp_f32_e32 v83, v83
	s_nop 0
	v_add_f32_e32 v83, 1.0, v83
	v_rcp_f32_e32 v84, v83
	v_mul_f32_e32 v83, 0xbfb8aa3b, v91
	v_exp_f32_e32 v83, v83
	s_nop 0
	v_add_f32_e32 v83, 1.0, v83
	v_rcp_f32_e32 v85, v83
	s_nop 0
	v_pk_mul_f32 v[84:85], v[90:91], v[84:85]
	s_nop 0
	v_pk_mul_f32 v[84:85], v[98:99], v[84:85]
	s_nop 0
	v_cvt_pk_bf16_f32 v83, v84, v85
	global_store_dwordx4 v[96:97], v[80:83], off
	s_nop 1
	v_pk_mul_f32 v[82:83], v[66:67], v[156:157] op_sel_hi:[1,0]
	v_pk_mul_f32 v[66:67], v[64:65], v[156:157] op_sel_hi:[1,0]
	v_mul_f32_e32 v64, 0xbfb8aa3b, v76
	v_mul_f32_e32 v65, 0xbfb8aa3b, v77
	v_exp_f32_e32 v64, v64
	v_exp_f32_e32 v65, v65
	v_mad_i64_i32 v[80:81], s[0:1], v200, s62, v[146:147]
	v_add_f32_e32 v64, 1.0, v64
	v_add_f32_e32 v65, 1.0, v65
	v_rcp_f32_e32 v64, v64
	v_rcp_f32_e32 v65, v65
	v_lshl_add_u64 v[80:81], v[80:81], 0, v[148:149]
	v_pk_mul_f32 v[64:65], v[76:77], v[64:65]
	s_nop 0
	v_pk_mul_f32 v[64:65], v[68:69], v[64:65]
	s_nop 0
	v_cvt_pk_bf16_f32 v64, v64, v65
	v_mul_f32_e32 v65, 0xbfb8aa3b, v78
	v_exp_f32_e32 v65, v65
	s_nop 0
	v_add_f32_e32 v65, 1.0, v65
	v_rcp_f32_e32 v68, v65
	v_mul_f32_e32 v65, 0xbfb8aa3b, v79
	v_exp_f32_e32 v65, v65
	s_nop 0
	v_add_f32_e32 v65, 1.0, v65
	v_rcp_f32_e32 v69, v65
	s_nop 0
	v_pk_mul_f32 v[68:69], v[78:79], v[68:69]
	s_nop 0
	v_pk_mul_f32 v[68:69], v[70:71], v[68:69]
	s_nop 0
	v_cvt_pk_bf16_f32 v65, v68, v69
	v_mul_f32_e32 v68, 0xbfb8aa3b, v72
	v_mul_f32_e32 v69, 0xbfb8aa3b, v73
	v_exp_f32_e32 v68, v68
	v_exp_f32_e32 v69, v69
	v_add_f32_e32 v68, 1.0, v68
	v_add_f32_e32 v69, 1.0, v69
	v_rcp_f32_e32 v68, v68
	v_rcp_f32_e32 v69, v69
	s_nop 0
	v_pk_mul_f32 v[68:69], v[72:73], v[68:69]
	s_nop 0
	v_pk_mul_f32 v[66:67], v[66:67], v[68:69]
	s_nop 0
	v_cvt_pk_bf16_f32 v66, v66, v67
	v_mul_f32_e32 v67, 0xbfb8aa3b, v74
	v_exp_f32_e32 v67, v67
	s_nop 0
	v_add_f32_e32 v67, 1.0, v67
	v_rcp_f32_e32 v68, v67
	v_mul_f32_e32 v67, 0xbfb8aa3b, v75
	v_exp_f32_e32 v67, v67
	s_nop 0
	v_add_f32_e32 v67, 1.0, v67
	v_rcp_f32_e32 v69, v67
	s_nop 0
	v_pk_mul_f32 v[68:69], v[74:75], v[68:69]
	s_nop 0
	v_pk_mul_f32 v[68:69], v[82:83], v[68:69]
	s_nop 0
	v_cvt_pk_bf16_f32 v67, v68, v69
	global_store_dwordx4 v[80:81], v[64:67], off
	s_nop 1
	v_pk_mul_f32 v[66:67], v[50:51], v[152:153] op_sel_hi:[1,0]
	v_pk_mul_f32 v[50:51], v[48:49], v[152:153] op_sel_hi:[1,0]
	v_mul_f32_e32 v48, 0xbfb8aa3b, v60
	v_mul_f32_e32 v49, 0xbfb8aa3b, v61
	v_exp_f32_e32 v48, v48
	v_exp_f32_e32 v49, v49
	v_mad_i64_i32 v[64:65], s[0:1], v198, s62, v[146:147]
	v_add_f32_e32 v48, 1.0, v48
	v_add_f32_e32 v49, 1.0, v49
	v_rcp_f32_e32 v48, v48
	v_rcp_f32_e32 v49, v49
	v_lshl_add_u64 v[64:65], v[64:65], 0, v[148:149]
	v_pk_mul_f32 v[48:49], v[60:61], v[48:49]
	s_nop 0
	v_pk_mul_f32 v[48:49], v[52:53], v[48:49]
	s_nop 0
	v_cvt_pk_bf16_f32 v48, v48, v49
	v_mul_f32_e32 v49, 0xbfb8aa3b, v62
	v_exp_f32_e32 v49, v49
	s_nop 0
	v_add_f32_e32 v49, 1.0, v49
	v_rcp_f32_e32 v52, v49
	v_mul_f32_e32 v49, 0xbfb8aa3b, v63
	v_exp_f32_e32 v49, v49
	s_nop 0
; #define PG8_BAR __builtin_amdgcn_s_barrier()
; #define GAS_ __attribute__((address_space(1)))
; __device__ __forceinline__ unsigned pk2(float lo, float hi) { f32x2_t v = {lo, hi}; bf16x2_t b = __builtin_convertvector(v, bf16x2_t); return __builtin_bit_cast(unsigned, b); }
; __device__ __forceinline__ float silu_f(float g) { return g * __builtin_amdgcn_rcpf(1.0f + __expf(-g)); }
; template <class Epi, class Sched, bool ALIGN_EPI = false, bool SP2 = false>
; __device__ __forceinline__ void gemm_phase(PG8_LAS unsigned char* lds, const Gemm g, const Sched& S, const Epi& E, int wave0) {
;     ...
;         if constexpr (ALIGN_EPI) { if (wr == 0) PG8_BAR; }
;         if constexpr (!Epi::AFTER_DRAIN) { E(acc, cur, wr, wc, fr, fq); S.done(cur); }
;         if (!has_next) break;
; #pragma unroll
;         for (int a = 0; a < 2; ++a)
; #pragma unroll
;             for (int b = 0; b < 2; ++b)
; #pragma unroll
;                 for (int m = 0; m < 4; ++m)
; #pragma unroll
;                     for (int n = 0; n < 2; ++n) acc[a][b][m][n] = (f32x4){0.f, 0.f, 0.f, 0.f};
;         cur = nxt; cA = nA; cB = nB; ++ui;
;         if constexpr (ALIGN_EPI) { if (wr == 1) PG8_BAR; }
;     __device__ __forceinline__ void operator()(const f32x4 (&acc)[2][2][4][2], const Unit& u, int wr, int wc, int fr, int fq) const {
;     ...
;                 bf16_t* rowp = H + (size_t)(row0 + ai * 128 + m * 16) * ldh + hc0;
;                 const float rs = rsv[ai][m];
;                 const f32x4 g0 = acc[ai][0][m][0] * rs, g1 = acc[ai][0][m][1] * rs, u0 = acc[ai][1][m][0] * rs, u1 = acc[ai][1][m][1] * rs;
;                 u32x4 w; w.x = pk2(silu_f(g0[0]) * u0[0], silu_f(g0[1]) * u0[1]); w.y = pk2(silu_f(g0[2]) * u0[2], silu_f(g0[3]) * u0[3]);
;                 w.z = pk2(silu_f(g1[0]) * u1[0], silu_f(g1[1]) * u1[1]); w.w = pk2(silu_f(g1[2]) * u1[2], silu_f(g1[3]) * u1[3]);
;                 *(GAS_ u32x4*)rowp = w;
;                 asm volatile("" ::: "memory");
;             }
	v_add_f32_e32 v49, 1.0, v49
	v_rcp_f32_e32 v53, v49
	s_nop 0
	v_pk_mul_f32 v[52:53], v[62:63], v[52:53]
	s_nop 0
	v_pk_mul_f32 v[52:53], v[54:55], v[52:53]
	s_nop 0
	v_cvt_pk_bf16_f32 v49, v52, v53
	v_mul_f32_e32 v52, 0xbfb8aa3b, v56
	v_mul_f32_e32 v53, 0xbfb8aa3b, v57
	v_exp_f32_e32 v52, v52
	v_exp_f32_e32 v53, v53
	v_add_f32_e32 v52, 1.0, v52
	v_add_f32_e32 v53, 1.0, v53
	v_rcp_f32_e32 v52, v52
	v_rcp_f32_e32 v53, v53
	s_nop 0
	v_pk_mul_f32 v[52:53], v[56:57], v[52:53]
	s_nop 0
	v_pk_mul_f32 v[50:51], v[50:51], v[52:53]
	s_nop 0
	v_cvt_pk_bf16_f32 v50, v50, v51
	v_mul_f32_e32 v51, 0xbfb8aa3b, v58
	v_exp_f32_e32 v51, v51
	s_nop 0
	v_add_f32_e32 v51, 1.0, v51
	v_rcp_f32_e32 v52, v51
	v_mul_f32_e32 v51, 0xbfb8aa3b, v59
	v_exp_f32_e32 v51, v51
	s_nop 0
	v_add_f32_e32 v51, 1.0, v51
	v_rcp_f32_e32 v53, v51
	s_nop 0
	v_pk_mul_f32 v[52:53], v[58:59], v[52:53]
	s_nop 0
	v_pk_mul_f32 v[52:53], v[66:67], v[52:53]
	s_nop 0
	v_cvt_pk_bf16_f32 v51, v52, v53
	global_store_dwordx4 v[64:65], v[48:51], off
	s_nop 1
	v_pk_mul_f32 v[50:51], v[34:35], v[150:151] op_sel_hi:[1,0]
	v_pk_mul_f32 v[34:35], v[32:33], v[150:151] op_sel_hi:[1,0]
	v_mul_f32_e32 v32, 0xbfb8aa3b, v44
	v_mul_f32_e32 v33, 0xbfb8aa3b, v45
	v_exp_f32_e32 v32, v32
	v_exp_f32_e32 v33, v33
	v_mad_i64_i32 v[48:49], s[0:1], v196, s62, v[146:147]
	v_add_f32_e32 v32, 1.0, v32
	v_add_f32_e32 v33, 1.0, v33
	v_rcp_f32_e32 v32, v32
	v_rcp_f32_e32 v33, v33
	v_lshl_add_u64 v[48:49], v[48:49], 0, v[148:149]
	v_pk_mul_f32 v[32:33], v[44:45], v[32:33]
	s_nop 0
	v_pk_mul_f32 v[32:33], v[36:37], v[32:33]
	s_nop 0
	v_cvt_pk_bf16_f32 v32, v32, v33
	v_mul_f32_e32 v33, 0xbfb8aa3b, v46
	v_exp_f32_e32 v33, v33
	s_nop 0
	v_add_f32_e32 v33, 1.0, v33
	v_rcp_f32_e32 v36, v33
	v_mul_f32_e32 v33, 0xbfb8aa3b, v47
	v_exp_f32_e32 v33, v33
	s_nop 0
	v_add_f32_e32 v33, 1.0, v33
	v_rcp_f32_e32 v37, v33
	s_nop 0
	v_pk_mul_f32 v[36:37], v[46:47], v[36:37]
	s_nop 0
	v_pk_mul_f32 v[36:37], v[38:39], v[36:37]
	s_nop 0
	v_cvt_pk_bf16_f32 v33, v36, v37
	v_mul_f32_e32 v36, 0xbfb8aa3b, v40
	v_mul_f32_e32 v37, 0xbfb8aa3b, v41
	v_exp_f32_e32 v36, v36
	v_exp_f32_e32 v37, v37
	v_add_f32_e32 v36, 1.0, v36
	v_add_f32_e32 v37, 1.0, v37
	v_rcp_f32_e32 v36, v36
	v_rcp_f32_e32 v37, v37
	s_nop 0
	v_pk_mul_f32 v[36:37], v[40:41], v[36:37]
	s_nop 0
	v_pk_mul_f32 v[34:35], v[34:35], v[36:37]
	s_nop 0
	v_cvt_pk_bf16_f32 v34, v34, v35
	v_mul_f32_e32 v35, 0xbfb8aa3b, v42
	v_exp_f32_e32 v35, v35
	s_nop 0
	v_add_f32_e32 v35, 1.0, v35
	v_rcp_f32_e32 v36, v35
	v_mul_f32_e32 v35, 0xbfb8aa3b, v43
	v_exp_f32_e32 v35, v35
	s_nop 0
	v_add_f32_e32 v35, 1.0, v35
	v_rcp_f32_e32 v37, v35
	s_nop 0
	v_pk_mul_f32 v[36:37], v[42:43], v[36:37]
	s_nop 0
	v_pk_mul_f32 v[36:37], v[50:51], v[36:37]
	s_nop 0
	v_cvt_pk_bf16_f32 v35, v36, v37
	global_store_dwordx4 v[48:49], v[32:35], off
	s_nop 1
	v_pk_mul_f32 v[34:35], v[18:19], v[144:145] op_sel_hi:[1,0]
	v_pk_mul_f32 v[18:19], v[16:17], v[144:145] op_sel_hi:[1,0]
	v_mul_f32_e32 v16, 0xbfb8aa3b, v28
	v_mul_f32_e32 v17, 0xbfb8aa3b, v29
	v_exp_f32_e32 v16, v16
	v_exp_f32_e32 v17, v17
	v_mad_i64_i32 v[32:33], s[0:1], v194, s62, v[146:147]
	v_add_f32_e32 v16, 1.0, v16
	v_add_f32_e32 v17, 1.0, v17
	v_rcp_f32_e32 v16, v16
	v_rcp_f32_e32 v17, v17
	v_lshl_add_u64 v[32:33], v[32:33], 0, v[148:149]
	s_mov_b64 s[0:1], -1
	v_pk_mul_f32 v[16:17], v[28:29], v[16:17]
	s_nop 0
	v_pk_mul_f32 v[16:17], v[20:21], v[16:17]
	s_nop 0
	v_cvt_pk_bf16_f32 v16, v16, v17
	v_mul_f32_e32 v17, 0xbfb8aa3b, v30
	v_exp_f32_e32 v17, v17
	s_nop 0
	v_add_f32_e32 v17, 1.0, v17
	v_rcp_f32_e32 v20, v17
	v_mul_f32_e32 v17, 0xbfb8aa3b, v31
	v_exp_f32_e32 v17, v17
	s_nop 0
	v_add_f32_e32 v17, 1.0, v17
	v_rcp_f32_e32 v21, v17
	s_nop 0
	v_pk_mul_f32 v[20:21], v[30:31], v[20:21]
	s_nop 0
	v_pk_mul_f32 v[20:21], v[22:23], v[20:21]
	s_nop 0
	v_cvt_pk_bf16_f32 v17, v20, v21
	v_mul_f32_e32 v20, 0xbfb8aa3b, v24
	v_mul_f32_e32 v21, 0xbfb8aa3b, v25
	v_exp_f32_e32 v20, v20
	v_exp_f32_e32 v21, v21
	v_add_f32_e32 v20, 1.0, v20
	v_add_f32_e32 v21, 1.0, v21
	v_rcp_f32_e32 v20, v20
	v_rcp_f32_e32 v21, v21
	s_nop 0
	v_pk_mul_f32 v[20:21], v[24:25], v[20:21]
	s_nop 0
	v_pk_mul_f32 v[18:19], v[18:19], v[20:21]
	s_nop 0
	v_cvt_pk_bf16_f32 v18, v18, v19
	v_mul_f32_e32 v19, 0xbfb8aa3b, v26
	v_exp_f32_e32 v19, v19
	s_nop 0
	v_add_f32_e32 v19, 1.0, v19
	v_rcp_f32_e32 v20, v19
	v_mul_f32_e32 v19, 0xbfb8aa3b, v27
	v_exp_f32_e32 v19, v19
	s_nop 0
	v_add_f32_e32 v19, 1.0, v19
	v_rcp_f32_e32 v21, v19
	s_nop 0
	v_pk_mul_f32 v[20:21], v[26:27], v[20:21]
	s_nop 0
	v_pk_mul_f32 v[20:21], v[34:35], v[20:21]
	s_nop 0
	v_cvt_pk_bf16_f32 v19, v20, v21
	global_store_dwordx4 v[32:33], v[16:19], off
	s_cbranch_vccnz .LBB0_1228
	s_andn2_b64 vcc, exec, s[10:11]
	s_cbranch_vccnz .LBB0_1227
	s_barrier
	v_readlane_b32 s98, v219, 0
	s_nop 1
	s_lshr_b32 s98, s98, 5
	s_and_b32 s99, s98, 1
	s_lshl_b32 s99, s99, 7
	s_lshr_b32 s100, s98, 1
	s_lshl_b32 s100, s100, 6
	s_add_i32 s99, s99, s100
	s_lshl_b32 s100, s18, 8
	s_add_i32 s99, s99, s100
	v_and_b32_e32 v16, 15, v217
	v_add_u32_e32 v16, s99, v16
	v_lshlrev_b32_e32 v16, 6, v16
	v_mov_b32_e32 v17, 0
	v_lshl_add_u64 v[16:17], v[188:189], 0, v[16:17]
	s_lshl_b32 s98, s98, 12
	s_add_i32 m0, s98, 0x24000
	s_nop 0
	global_load_lds_dwordx4 v[16:17], off
	global_load_lds_dwordx4 v[16:17], off offset:1024
	global_load_lds_dwordx4 v[16:17], off offset:2048
	global_load_lds_dwordx4 v[16:17], off offset:3072
	s_branch .LBB0_1227

; __global__ void __launch_bounds__(512, 2) fwd_mega(Params P) {
;     extern __shared__ __attribute__((aligned(16))) unsigned char lds_raw[];
	.amdhsa_kernel _Z8fwd_mega6Params
		.amdhsa_group_segment_fixed_size 16384
		.amdhsa_private_segment_fixed_size 0
		.amdhsa_kernarg_size 536
		.amdhsa_user_sgpr_count 2
		.amdhsa_user_sgpr_dispatch_ptr 0
		.amdhsa_user_sgpr_queue_ptr 0
		.amdhsa_user_sgpr_kernarg_segment_ptr 1
		.amdhsa_user_sgpr_dispatch_id 0
		.amdhsa_user_sgpr_kernarg_preload_length 0
		.amdhsa_user_sgpr_kernarg_preload_offset 0
		.amdhsa_user_sgpr_private_segment_size 0
		.amdhsa_uses_dynamic_stack 0
		.amdhsa_enable_private_segment 0
		.amdhsa_system_sgpr_workgroup_id_x 1
		.amdhsa_system_sgpr_workgroup_id_y 0
		.amdhsa_system_sgpr_workgroup_id_z 0
		.amdhsa_system_sgpr_workgroup_info 0
		.amdhsa_system_vgpr_workitem_id 2
		.amdhsa_next_free_vgpr 256
		.amdhsa_next_free_sgpr 102
		.amdhsa_accum_offset 256
		.amdhsa_reserve_vcc 1
		.amdhsa_float_round_mode_32 0
		.amdhsa_float_round_mode_16_64 0
		.amdhsa_float_denorm_mode_32 3
		.amdhsa_float_denorm_mode_16_64 3
		.amdhsa_dx10_clamp 1
		.amdhsa_ieee_mode 1
		.amdhsa_fp16_overflow 0
		.amdhsa_tg_split 0
		.amdhsa_exception_fp_ieee_invalid_op 0
		.amdhsa_exception_fp_denorm_src 0
		.amdhsa_exception_fp_ieee_div_zero 0
		.amdhsa_exception_fp_ieee_overflow 0
		.amdhsa_exception_fp_ieee_underflow 0
		.amdhsa_exception_fp_ieee_inexact 0
		.amdhsa_exception_int_div_zero 0
	.end_amdhsa_kernel

; __global__ void __launch_bounds__(512, 2) fwd_mega(Params P) {
;     extern __shared__ __attribute__((aligned(16))) unsigned char lds_raw[];
amdhsa.kernels:
  - .agpr_count:     0
    .args:
      - .offset:         0
        .size:           280
        .value_kind:     by_value
      - .offset:         280
        .size:           4
        .value_kind:     hidden_block_count_x
      - .offset:         284
        .size:           4
        .value_kind:     hidden_block_count_y
      - .offset:         288
        .size:           4
        .value_kind:     hidden_block_count_z
      - .offset:         292
        .size:           2
        .value_kind:     hidden_group_size_x
      - .offset:         294
        .size:           2
        .value_kind:     hidden_group_size_y
      - .offset:         296
        .size:           2
        .value_kind:     hidden_group_size_z
      - .offset:         298
        .size:           2
        .value_kind:     hidden_remainder_x
      - .offset:         300
        .size:           2
        .value_kind:     hidden_remainder_y
      - .offset:         302
        .size:           2
        .value_kind:     hidden_remainder_z
      - .offset:         320
        .size:           8
        .value_kind:     hidden_global_offset_x
      - .offset:         328
        .size:           8
        .value_kind:     hidden_global_offset_y
      - .offset:         336
        .size:           8
        .value_kind:     hidden_global_offset_z
      - .offset:         344
        .size:           2
        .value_kind:     hidden_grid_dims
      - .offset:         368
        .size:           8
        .value_kind:     hidden_multigrid_sync_arg
      - .offset:         400
        .size:           4
        .value_kind:     hidden_dynamic_lds_size
    .group_segment_fixed_size: 16384
    .kernarg_segment_align: 8
    .kernarg_segment_size: 536
    .language:       OpenCL C
    .language_version:
      - 2
      - 0
    .max_flat_workgroup_size: 512
    .name:           _Z8fwd_mega6Params
    .private_segment_fixed_size: 0
    .sgpr_count:     108
    .sgpr_spill_count: 658
    .symbol:         _Z8fwd_mega6Params.kd
    .uniform_work_group_size: 1
    .uses_dynamic_stack: false
    .vgpr_count:     256
    .vgpr_spill_count: 0
    .wavefront_size: 64
